# v69 + per-tile accumulator zeroing done with 64 v_mov_b64 (literal 0) instead of 128 v_mov_b32 in 8 GEMM tile loops
# baseline (speedup 1.0000x reference)
.Lzskip_1:
	s_add_u32 s20, s20, 0x80
	s_addc_u32 s21, s21, 0
	s_add_u32 s52, s22, 0x100
	s_addc_u32 s53, s23, 0
	s_mov_b32 s22, 0
	v_mov_b64_e32 v[0:1], 0
	v_mov_b64_e32 v[2:3], 0
	v_mov_b64_e32 v[4:5], 0
	v_mov_b64_e32 v[6:7], 0
	v_mov_b64_e32 v[8:9], 0
	v_mov_b64_e32 v[10:11], 0
	v_mov_b64_e32 v[12:13], 0
	v_mov_b64_e32 v[14:15], 0
	v_mov_b64_e32 v[16:17], 0
	v_mov_b64_e32 v[18:19], 0
	v_mov_b64_e32 v[20:21], 0
	v_mov_b64_e32 v[22:23], 0
	v_mov_b64_e32 v[24:25], 0
	v_mov_b64_e32 v[26:27], 0
	v_mov_b64_e32 v[28:29], 0
	v_mov_b64_e32 v[30:31], 0
	v_mov_b64_e32 v[32:33], 0
	v_mov_b64_e32 v[34:35], 0
	v_mov_b64_e32 v[36:37], 0
	v_mov_b64_e32 v[38:39], 0
	v_mov_b64_e32 v[40:41], 0
	v_mov_b64_e32 v[42:43], 0
	v_mov_b64_e32 v[44:45], 0
	v_mov_b64_e32 v[46:47], 0
	v_mov_b64_e32 v[48:49], 0
	v_mov_b64_e32 v[50:51], 0
	v_mov_b64_e32 v[52:53], 0
	v_mov_b64_e32 v[54:55], 0
	v_mov_b64_e32 v[56:57], 0
	v_mov_b64_e32 v[58:59], 0
	v_mov_b64_e32 v[60:61], 0
	v_mov_b64_e32 v[62:63], 0
	v_mov_b64_e32 v[64:65], 0
	v_mov_b64_e32 v[66:67], 0
	v_mov_b64_e32 v[68:69], 0
	v_mov_b64_e32 v[70:71], 0
	v_mov_b64_e32 v[72:73], 0
	v_mov_b64_e32 v[74:75], 0
	v_mov_b64_e32 v[76:77], 0
	v_mov_b64_e32 v[78:79], 0
	v_mov_b64_e32 v[80:81], 0
	v_mov_b64_e32 v[82:83], 0
	v_mov_b64_e32 v[84:85], 0
	v_mov_b64_e32 v[86:87], 0
	v_mov_b64_e32 v[88:89], 0
	v_mov_b64_e32 v[90:91], 0
	v_mov_b64_e32 v[92:93], 0
	v_mov_b64_e32 v[94:95], 0
	v_mov_b64_e32 v[96:97], 0
	v_mov_b64_e32 v[98:99], 0
	v_mov_b64_e32 v[100:101], 0
	v_mov_b64_e32 v[102:103], 0
	v_mov_b64_e32 v[104:105], 0
	v_mov_b64_e32 v[106:107], 0
	v_mov_b64_e32 v[108:109], 0
	v_mov_b64_e32 v[110:111], 0
	v_mov_b64_e32 v[112:113], 0
	v_mov_b64_e32 v[114:115], 0
	v_mov_b64_e32 v[116:117], 0
	v_mov_b64_e32 v[118:119], 0
	v_mov_b64_e32 v[120:121], 0
	v_mov_b64_e32 v[122:123], 0
	v_mov_b64_e32 v[124:125], 0
	v_mov_b64_e32 v[126:127], 0

.Lzskip_2:
	s_add_u32 s0, s52, 0x80
	s_addc_u32 s1, s53, 0
	s_add_u32 s33, s50, 0x100
	s_addc_u32 s52, s51, 0
	s_mov_b32 s50, 0
	v_mov_b64_e32 v[0:1], 0
	v_mov_b64_e32 v[2:3], 0
	v_mov_b64_e32 v[4:5], 0
	v_mov_b64_e32 v[6:7], 0
	v_mov_b64_e32 v[8:9], 0
	v_mov_b64_e32 v[10:11], 0
	v_mov_b64_e32 v[12:13], 0
	v_mov_b64_e32 v[14:15], 0
	v_mov_b64_e32 v[16:17], 0
	v_mov_b64_e32 v[18:19], 0
	v_mov_b64_e32 v[20:21], 0
	v_mov_b64_e32 v[22:23], 0
	v_mov_b64_e32 v[24:25], 0
	v_mov_b64_e32 v[26:27], 0
	v_mov_b64_e32 v[28:29], 0
	v_mov_b64_e32 v[30:31], 0
	v_mov_b64_e32 v[32:33], 0
	v_mov_b64_e32 v[34:35], 0
	v_mov_b64_e32 v[36:37], 0
	v_mov_b64_e32 v[38:39], 0
	v_mov_b64_e32 v[40:41], 0
	v_mov_b64_e32 v[42:43], 0
	v_mov_b64_e32 v[44:45], 0
	v_mov_b64_e32 v[46:47], 0
	v_mov_b64_e32 v[48:49], 0
	v_mov_b64_e32 v[50:51], 0
	v_mov_b64_e32 v[52:53], 0
	v_mov_b64_e32 v[54:55], 0
	v_mov_b64_e32 v[56:57], 0
	v_mov_b64_e32 v[58:59], 0
	v_mov_b64_e32 v[60:61], 0
	v_mov_b64_e32 v[62:63], 0
	v_mov_b64_e32 v[64:65], 0
	v_mov_b64_e32 v[66:67], 0
	v_mov_b64_e32 v[68:69], 0
	v_mov_b64_e32 v[70:71], 0
	v_mov_b64_e32 v[72:73], 0
	v_mov_b64_e32 v[74:75], 0
	v_mov_b64_e32 v[76:77], 0
	v_mov_b64_e32 v[78:79], 0
	v_mov_b64_e32 v[80:81], 0
	v_mov_b64_e32 v[82:83], 0
	v_mov_b64_e32 v[84:85], 0
	v_mov_b64_e32 v[86:87], 0
	v_mov_b64_e32 v[88:89], 0
	v_mov_b64_e32 v[90:91], 0
	v_mov_b64_e32 v[92:93], 0
	v_mov_b64_e32 v[94:95], 0
	v_mov_b64_e32 v[96:97], 0
	v_mov_b64_e32 v[98:99], 0
	v_mov_b64_e32 v[100:101], 0
	v_mov_b64_e32 v[102:103], 0
	v_mov_b64_e32 v[104:105], 0
	v_mov_b64_e32 v[106:107], 0
	v_mov_b64_e32 v[108:109], 0
	v_mov_b64_e32 v[110:111], 0
	v_mov_b64_e32 v[112:113], 0
	v_mov_b64_e32 v[114:115], 0
	v_mov_b64_e32 v[116:117], 0
	v_mov_b64_e32 v[118:119], 0
	v_mov_b64_e32 v[120:121], 0
	v_mov_b64_e32 v[122:123], 0
	v_mov_b64_e32 v[124:125], 0
	v_mov_b64_e32 v[126:127], 0

.Lzskip_3:
	s_add_u32 s30, s30, 0x80
	s_addc_u32 s31, s31, 0
	s_add_u32 s62, s34, 0x100
	s_addc_u32 s63, s35, 0
	s_mov_b32 s34, 0
	v_mov_b64_e32 v[0:1], 0
	v_mov_b64_e32 v[2:3], 0
	v_mov_b64_e32 v[4:5], 0
	v_mov_b64_e32 v[6:7], 0
	v_mov_b64_e32 v[8:9], 0
	v_mov_b64_e32 v[10:11], 0
	v_mov_b64_e32 v[12:13], 0
	v_mov_b64_e32 v[14:15], 0
	v_mov_b64_e32 v[16:17], 0
	v_mov_b64_e32 v[18:19], 0
	v_mov_b64_e32 v[20:21], 0
	v_mov_b64_e32 v[22:23], 0
	v_mov_b64_e32 v[24:25], 0
	v_mov_b64_e32 v[26:27], 0
	v_mov_b64_e32 v[28:29], 0
	v_mov_b64_e32 v[30:31], 0
	v_mov_b64_e32 v[32:33], 0
	v_mov_b64_e32 v[34:35], 0
	v_mov_b64_e32 v[36:37], 0
	v_mov_b64_e32 v[38:39], 0
	v_mov_b64_e32 v[40:41], 0
	v_mov_b64_e32 v[42:43], 0
	v_mov_b64_e32 v[44:45], 0
	v_mov_b64_e32 v[46:47], 0
	v_mov_b64_e32 v[48:49], 0
	v_mov_b64_e32 v[50:51], 0
	v_mov_b64_e32 v[52:53], 0
	v_mov_b64_e32 v[54:55], 0
	v_mov_b64_e32 v[56:57], 0
	v_mov_b64_e32 v[58:59], 0
	v_mov_b64_e32 v[60:61], 0
	v_mov_b64_e32 v[62:63], 0
	v_mov_b64_e32 v[64:65], 0
	v_mov_b64_e32 v[66:67], 0
	v_mov_b64_e32 v[68:69], 0
	v_mov_b64_e32 v[70:71], 0
	v_mov_b64_e32 v[72:73], 0
	v_mov_b64_e32 v[74:75], 0
	v_mov_b64_e32 v[76:77], 0
	v_mov_b64_e32 v[78:79], 0
	v_mov_b64_e32 v[80:81], 0
	v_mov_b64_e32 v[82:83], 0
	v_mov_b64_e32 v[84:85], 0
	v_mov_b64_e32 v[86:87], 0
	v_mov_b64_e32 v[88:89], 0
	v_mov_b64_e32 v[90:91], 0
	v_mov_b64_e32 v[92:93], 0
	v_mov_b64_e32 v[94:95], 0
	v_mov_b64_e32 v[96:97], 0
	v_mov_b64_e32 v[98:99], 0
	v_mov_b64_e32 v[100:101], 0
	v_mov_b64_e32 v[102:103], 0
	v_mov_b64_e32 v[104:105], 0
	v_mov_b64_e32 v[106:107], 0
	v_mov_b64_e32 v[108:109], 0
	v_mov_b64_e32 v[110:111], 0
	v_mov_b64_e32 v[112:113], 0
	v_mov_b64_e32 v[114:115], 0
	v_mov_b64_e32 v[116:117], 0
	v_mov_b64_e32 v[118:119], 0
	v_mov_b64_e32 v[120:121], 0
	v_mov_b64_e32 v[122:123], 0
	v_mov_b64_e32 v[124:125], 0
	v_mov_b64_e32 v[126:127], 0

.Lzskip_4:
	s_add_u32 s24, s24, 0x80
	s_addc_u32 s25, s25, 0
	s_add_u32 s52, s26, 0x100
	s_addc_u32 s53, s27, 0
	s_mov_b32 s26, 0
	v_mov_b64_e32 v[0:1], 0
	v_mov_b64_e32 v[2:3], 0
	v_mov_b64_e32 v[4:5], 0
	v_mov_b64_e32 v[6:7], 0
	v_mov_b64_e32 v[8:9], 0
	v_mov_b64_e32 v[10:11], 0
	v_mov_b64_e32 v[12:13], 0
	v_mov_b64_e32 v[14:15], 0
	v_mov_b64_e32 v[16:17], 0
	v_mov_b64_e32 v[18:19], 0
	v_mov_b64_e32 v[20:21], 0
	v_mov_b64_e32 v[22:23], 0
	v_mov_b64_e32 v[24:25], 0
	v_mov_b64_e32 v[26:27], 0
	v_mov_b64_e32 v[28:29], 0
	v_mov_b64_e32 v[30:31], 0
	v_mov_b64_e32 v[32:33], 0
	v_mov_b64_e32 v[34:35], 0
	v_mov_b64_e32 v[36:37], 0
	v_mov_b64_e32 v[38:39], 0
	v_mov_b64_e32 v[40:41], 0
	v_mov_b64_e32 v[42:43], 0
	v_mov_b64_e32 v[44:45], 0
	v_mov_b64_e32 v[46:47], 0
	v_mov_b64_e32 v[48:49], 0
	v_mov_b64_e32 v[50:51], 0
	v_mov_b64_e32 v[52:53], 0
	v_mov_b64_e32 v[54:55], 0
	v_mov_b64_e32 v[56:57], 0
	v_mov_b64_e32 v[58:59], 0
	v_mov_b64_e32 v[60:61], 0
	v_mov_b64_e32 v[62:63], 0
	v_mov_b64_e32 v[64:65], 0
	v_mov_b64_e32 v[66:67], 0
	v_mov_b64_e32 v[68:69], 0
	v_mov_b64_e32 v[70:71], 0
	v_mov_b64_e32 v[72:73], 0
	v_mov_b64_e32 v[74:75], 0
	v_mov_b64_e32 v[76:77], 0
	v_mov_b64_e32 v[78:79], 0
	v_mov_b64_e32 v[80:81], 0
	v_mov_b64_e32 v[82:83], 0
	v_mov_b64_e32 v[84:85], 0
	v_mov_b64_e32 v[86:87], 0
	v_mov_b64_e32 v[88:89], 0
	v_mov_b64_e32 v[90:91], 0
	v_mov_b64_e32 v[92:93], 0
	v_mov_b64_e32 v[94:95], 0
	v_mov_b64_e32 v[96:97], 0
	v_mov_b64_e32 v[98:99], 0
	v_mov_b64_e32 v[100:101], 0
	v_mov_b64_e32 v[102:103], 0
	v_mov_b64_e32 v[104:105], 0
	v_mov_b64_e32 v[106:107], 0
	v_mov_b64_e32 v[108:109], 0
	v_mov_b64_e32 v[110:111], 0
	v_mov_b64_e32 v[112:113], 0
	v_mov_b64_e32 v[114:115], 0
	v_mov_b64_e32 v[116:117], 0
	v_mov_b64_e32 v[118:119], 0
	v_mov_b64_e32 v[120:121], 0
	v_mov_b64_e32 v[122:123], 0
	v_mov_b64_e32 v[124:125], 0
	v_mov_b64_e32 v[126:127], 0

.Lzskip_5:
	s_add_u32 s28, s28, 0x80
	s_addc_u32 s29, s29, 0
	s_add_u32 s60, s30, 0x100
	s_addc_u32 s61, s31, 0
	s_mov_b32 s30, 0
	v_mov_b64_e32 v[0:1], 0
	v_mov_b64_e32 v[2:3], 0
	v_mov_b64_e32 v[4:5], 0
	v_mov_b64_e32 v[6:7], 0
	v_mov_b64_e32 v[8:9], 0
	v_mov_b64_e32 v[10:11], 0
	v_mov_b64_e32 v[12:13], 0
	v_mov_b64_e32 v[14:15], 0
	v_mov_b64_e32 v[16:17], 0
	v_mov_b64_e32 v[18:19], 0
	v_mov_b64_e32 v[20:21], 0
	v_mov_b64_e32 v[22:23], 0
	v_mov_b64_e32 v[24:25], 0
	v_mov_b64_e32 v[26:27], 0
	v_mov_b64_e32 v[28:29], 0
	v_mov_b64_e32 v[30:31], 0
	v_mov_b64_e32 v[32:33], 0
	v_mov_b64_e32 v[34:35], 0
	v_mov_b64_e32 v[36:37], 0
	v_mov_b64_e32 v[38:39], 0
	v_mov_b64_e32 v[40:41], 0
	v_mov_b64_e32 v[42:43], 0
	v_mov_b64_e32 v[44:45], 0
	v_mov_b64_e32 v[46:47], 0
	v_mov_b64_e32 v[48:49], 0
	v_mov_b64_e32 v[50:51], 0
	v_mov_b64_e32 v[52:53], 0
	v_mov_b64_e32 v[54:55], 0
	v_mov_b64_e32 v[56:57], 0
	v_mov_b64_e32 v[58:59], 0
	v_mov_b64_e32 v[60:61], 0
	v_mov_b64_e32 v[62:63], 0
	v_mov_b64_e32 v[64:65], 0
	v_mov_b64_e32 v[66:67], 0
	v_mov_b64_e32 v[68:69], 0
	v_mov_b64_e32 v[70:71], 0
	v_mov_b64_e32 v[72:73], 0
	v_mov_b64_e32 v[74:75], 0
	v_mov_b64_e32 v[76:77], 0
	v_mov_b64_e32 v[78:79], 0
	v_mov_b64_e32 v[80:81], 0
	v_mov_b64_e32 v[82:83], 0
	v_mov_b64_e32 v[84:85], 0
	v_mov_b64_e32 v[86:87], 0
	v_mov_b64_e32 v[88:89], 0
	v_mov_b64_e32 v[90:91], 0
	v_mov_b64_e32 v[92:93], 0
	v_mov_b64_e32 v[94:95], 0
	v_mov_b64_e32 v[96:97], 0
	v_mov_b64_e32 v[98:99], 0
	v_mov_b64_e32 v[100:101], 0
	v_mov_b64_e32 v[102:103], 0
	v_mov_b64_e32 v[104:105], 0
	v_mov_b64_e32 v[106:107], 0
	v_mov_b64_e32 v[108:109], 0
	v_mov_b64_e32 v[110:111], 0
	v_mov_b64_e32 v[124:125], 0
	v_mov_b64_e32 v[126:127], 0
	v_mov_b64_e32 v[132:133], 0
	v_mov_b64_e32 v[134:135], 0
	v_mov_b64_e32 v[136:137], 0
	v_mov_b64_e32 v[138:139], 0
	v_mov_b64_e32 v[140:141], 0
	v_mov_b64_e32 v[142:143], 0

.Lzskip_6:
	s_add_u32 s30, s30, 0x80
	s_addc_u32 s31, s31, 0
	s_add_u32 s66, s34, 0x100
	s_addc_u32 s67, s35, 0
	s_mov_b32 s34, 0
	v_mov_b64_e32 v[0:1], 0
	v_mov_b64_e32 v[2:3], 0
	v_mov_b64_e32 v[4:5], 0
	v_mov_b64_e32 v[6:7], 0
	v_mov_b64_e32 v[8:9], 0
	v_mov_b64_e32 v[10:11], 0
	v_mov_b64_e32 v[12:13], 0
	v_mov_b64_e32 v[14:15], 0
	v_mov_b64_e32 v[16:17], 0
	v_mov_b64_e32 v[18:19], 0
	v_mov_b64_e32 v[20:21], 0
	v_mov_b64_e32 v[22:23], 0
	v_mov_b64_e32 v[24:25], 0
	v_mov_b64_e32 v[26:27], 0
	v_mov_b64_e32 v[28:29], 0
	v_mov_b64_e32 v[30:31], 0
	v_mov_b64_e32 v[32:33], 0
	v_mov_b64_e32 v[34:35], 0
	v_mov_b64_e32 v[36:37], 0
	v_mov_b64_e32 v[38:39], 0
	v_mov_b64_e32 v[40:41], 0
	v_mov_b64_e32 v[42:43], 0
	v_mov_b64_e32 v[44:45], 0
	v_mov_b64_e32 v[46:47], 0
	v_mov_b64_e32 v[48:49], 0
	v_mov_b64_e32 v[50:51], 0
	v_mov_b64_e32 v[52:53], 0
	v_mov_b64_e32 v[54:55], 0
	v_mov_b64_e32 v[56:57], 0
	v_mov_b64_e32 v[58:59], 0
	v_mov_b64_e32 v[60:61], 0
	v_mov_b64_e32 v[62:63], 0
	v_mov_b64_e32 v[64:65], 0
	v_mov_b64_e32 v[66:67], 0
	v_mov_b64_e32 v[68:69], 0
	v_mov_b64_e32 v[70:71], 0
	v_mov_b64_e32 v[72:73], 0
	v_mov_b64_e32 v[74:75], 0
	v_mov_b64_e32 v[76:77], 0
	v_mov_b64_e32 v[78:79], 0
	v_mov_b64_e32 v[80:81], 0
	v_mov_b64_e32 v[82:83], 0
	v_mov_b64_e32 v[84:85], 0
	v_mov_b64_e32 v[86:87], 0
	v_mov_b64_e32 v[88:89], 0
	v_mov_b64_e32 v[90:91], 0
	v_mov_b64_e32 v[92:93], 0
	v_mov_b64_e32 v[94:95], 0
	v_mov_b64_e32 v[96:97], 0
	v_mov_b64_e32 v[98:99], 0
	v_mov_b64_e32 v[100:101], 0
	v_mov_b64_e32 v[102:103], 0
	v_mov_b64_e32 v[104:105], 0
	v_mov_b64_e32 v[106:107], 0
	v_mov_b64_e32 v[108:109], 0
	v_mov_b64_e32 v[110:111], 0
	v_mov_b64_e32 v[112:113], 0
	v_mov_b64_e32 v[114:115], 0
	v_mov_b64_e32 v[116:117], 0
	v_mov_b64_e32 v[118:119], 0
	v_mov_b64_e32 v[120:121], 0
	v_mov_b64_e32 v[122:123], 0
	v_mov_b64_e32 v[124:125], 0
	v_mov_b64_e32 v[126:127], 0

.Lzskip_7:
	s_add_u32 s2, s6, 0x80
	s_addc_u32 s3, s7, 0
	s_add_u32 s6, s4, 0x100
	s_addc_u32 s7, s5, 0
	s_mov_b32 s4, 0
	v_mov_b64_e32 v[0:1], 0
	v_mov_b64_e32 v[2:3], 0
	v_mov_b64_e32 v[4:5], 0
	v_mov_b64_e32 v[6:7], 0
	v_mov_b64_e32 v[8:9], 0
	v_mov_b64_e32 v[10:11], 0
	v_mov_b64_e32 v[12:13], 0
	v_mov_b64_e32 v[14:15], 0
	v_mov_b64_e32 v[16:17], 0
	v_mov_b64_e32 v[18:19], 0
	v_mov_b64_e32 v[20:21], 0
	v_mov_b64_e32 v[22:23], 0
	v_mov_b64_e32 v[24:25], 0
	v_mov_b64_e32 v[26:27], 0
	v_mov_b64_e32 v[28:29], 0
	v_mov_b64_e32 v[30:31], 0
	v_mov_b64_e32 v[32:33], 0
	v_mov_b64_e32 v[34:35], 0
	v_mov_b64_e32 v[36:37], 0
	v_mov_b64_e32 v[38:39], 0
	v_mov_b64_e32 v[40:41], 0
	v_mov_b64_e32 v[42:43], 0
	v_mov_b64_e32 v[44:45], 0
	v_mov_b64_e32 v[46:47], 0
	v_mov_b64_e32 v[48:49], 0
	v_mov_b64_e32 v[50:51], 0
	v_mov_b64_e32 v[52:53], 0
	v_mov_b64_e32 v[54:55], 0
	v_mov_b64_e32 v[56:57], 0
	v_mov_b64_e32 v[58:59], 0
	v_mov_b64_e32 v[60:61], 0
	v_mov_b64_e32 v[62:63], 0
	v_mov_b64_e32 v[64:65], 0
	v_mov_b64_e32 v[66:67], 0
	v_mov_b64_e32 v[68:69], 0
	v_mov_b64_e32 v[70:71], 0
	v_mov_b64_e32 v[72:73], 0
	v_mov_b64_e32 v[74:75], 0
	v_mov_b64_e32 v[76:77], 0
	v_mov_b64_e32 v[78:79], 0
	v_mov_b64_e32 v[80:81], 0
	v_mov_b64_e32 v[82:83], 0
	v_mov_b64_e32 v[84:85], 0
	v_mov_b64_e32 v[86:87], 0
	v_mov_b64_e32 v[88:89], 0
	v_mov_b64_e32 v[90:91], 0
	v_mov_b64_e32 v[92:93], 0
	v_mov_b64_e32 v[94:95], 0
	v_mov_b64_e32 v[96:97], 0
	v_mov_b64_e32 v[98:99], 0
	v_mov_b64_e32 v[100:101], 0
	v_mov_b64_e32 v[102:103], 0
	v_mov_b64_e32 v[104:105], 0
	v_mov_b64_e32 v[106:107], 0
	v_mov_b64_e32 v[108:109], 0
	v_mov_b64_e32 v[110:111], 0
	v_mov_b64_e32 v[112:113], 0
	v_mov_b64_e32 v[114:115], 0
	v_mov_b64_e32 v[116:117], 0
	v_mov_b64_e32 v[118:119], 0
	v_mov_b64_e32 v[120:121], 0
	v_mov_b64_e32 v[122:123], 0
	v_mov_b64_e32 v[124:125], 0
	v_mov_b64_e32 v[126:127], 0

.Lzskip_8:
	s_add_u32 s0, s38, 0x80
	s_addc_u32 s1, s39, 0
	s_add_u32 s38, s6, 0x100
	s_addc_u32 s39, s7, 0
	s_mov_b32 s6, 0
	v_mov_b64_e32 v[0:1], 0
	v_mov_b64_e32 v[2:3], 0
	v_mov_b64_e32 v[4:5], 0
	v_mov_b64_e32 v[6:7], 0
	v_mov_b64_e32 v[8:9], 0
	v_mov_b64_e32 v[10:11], 0
	v_mov_b64_e32 v[12:13], 0
	v_mov_b64_e32 v[14:15], 0
	v_mov_b64_e32 v[16:17], 0
	v_mov_b64_e32 v[18:19], 0
	v_mov_b64_e32 v[20:21], 0
	v_mov_b64_e32 v[22:23], 0
	v_mov_b64_e32 v[24:25], 0
	v_mov_b64_e32 v[26:27], 0
	v_mov_b64_e32 v[28:29], 0
	v_mov_b64_e32 v[30:31], 0
	v_mov_b64_e32 v[32:33], 0
	v_mov_b64_e32 v[34:35], 0
	v_mov_b64_e32 v[36:37], 0
	v_mov_b64_e32 v[38:39], 0
	v_mov_b64_e32 v[40:41], 0
	v_mov_b64_e32 v[42:43], 0
	v_mov_b64_e32 v[44:45], 0
	v_mov_b64_e32 v[46:47], 0
	v_mov_b64_e32 v[48:49], 0
	v_mov_b64_e32 v[50:51], 0
	v_mov_b64_e32 v[52:53], 0
	v_mov_b64_e32 v[54:55], 0
	v_mov_b64_e32 v[56:57], 0
	v_mov_b64_e32 v[58:59], 0
	v_mov_b64_e32 v[60:61], 0
	v_mov_b64_e32 v[62:63], 0
	v_mov_b64_e32 v[64:65], 0
	v_mov_b64_e32 v[66:67], 0
	v_mov_b64_e32 v[68:69], 0
	v_mov_b64_e32 v[70:71], 0
	v_mov_b64_e32 v[72:73], 0
	v_mov_b64_e32 v[74:75], 0
	v_mov_b64_e32 v[76:77], 0
	v_mov_b64_e32 v[78:79], 0
	v_mov_b64_e32 v[80:81], 0
	v_mov_b64_e32 v[82:83], 0
	v_mov_b64_e32 v[84:85], 0
	v_mov_b64_e32 v[86:87], 0
	v_mov_b64_e32 v[88:89], 0
	v_mov_b64_e32 v[90:91], 0
	v_mov_b64_e32 v[92:93], 0
	v_mov_b64_e32 v[94:95], 0
	v_mov_b64_e32 v[96:97], 0
	v_mov_b64_e32 v[98:99], 0
	v_mov_b64_e32 v[100:101], 0
	v_mov_b64_e32 v[102:103], 0
	v_mov_b64_e32 v[104:105], 0
	v_mov_b64_e32 v[106:107], 0
	v_mov_b64_e32 v[108:109], 0
	v_mov_b64_e32 v[110:111], 0
	v_mov_b64_e32 v[112:113], 0
	v_mov_b64_e32 v[114:115], 0
	v_mov_b64_e32 v[116:117], 0
	v_mov_b64_e32 v[118:119], 0
	v_mov_b64_e32 v[120:121], 0
	v_mov_b64_e32 v[122:123], 0
	v_mov_b64_e32 v[124:125], 0
	v_mov_b64_e32 v[126:127], 0
